# gemm160 epilogues: v_permlane16_swap pairs 8-byte column groups into 16-byte stores (20 dwordx2 -> 10 dwordx4 per lane), gemm_in bounds mask hoisted to one wave-uniform exec mask
# speedup vs baseline: 1.0453x; 1.0152x over previous
.Lg160i_epi:
	v_lshl_add_u32 v88, s6, 8, v105
	s_mulk_i32 s15, 0xa0
	v_or_b32_e32 v92, s15, v94
	v_ashrrev_i32_e32 v89, 31, v88
	v_mad_i64_i32 v[90:91], s[6:7], v92, s67, v[88:89]
	s_barrier
	v_cmp_gt_i32_e32 vcc, s67, v88
	v_lshl_add_u64 v[90:91], v[90:91], 1, s[8:9]
	v_bfe_u32 v88, v222, 4, 1
	v_mul_u32_u24_e32 v88, 24, v88
	v_mov_b32_e32 v89, 0
	v_lshl_add_u64 v[90:91], v[88:89], 0, v[90:91]
	s_mov_b64 s[12:13], 0x9400
	v_cvt_pk_bf16_f32 v76, v76, v77
	v_cvt_pk_bf16_f32 v77, v78, v79
	v_cvt_pk_bf16_f32 v78, v72, v73
	v_cvt_pk_bf16_f32 v79, v74, v75
	s_nop 1
	v_permlane16_swap_b32_e32 v76, v78
	v_permlane16_swap_b32_e32 v77, v79
	v_cvt_pk_bf16_f32 v68, v68, v69
	v_cvt_pk_bf16_f32 v69, v70, v71
	v_cvt_pk_bf16_f32 v70, v64, v65
	v_cvt_pk_bf16_f32 v71, v66, v67
	s_nop 1
	v_permlane16_swap_b32_e32 v68, v70
	v_permlane16_swap_b32_e32 v69, v71
	v_cvt_pk_bf16_f32 v60, v60, v61
	v_cvt_pk_bf16_f32 v61, v62, v63
	v_cvt_pk_bf16_f32 v62, v56, v57
	v_cvt_pk_bf16_f32 v63, v58, v59
	s_nop 1
	v_permlane16_swap_b32_e32 v60, v62
	v_permlane16_swap_b32_e32 v61, v63
	v_cvt_pk_bf16_f32 v52, v52, v53
	v_cvt_pk_bf16_f32 v53, v54, v55
	v_cvt_pk_bf16_f32 v54, v48, v49
	v_cvt_pk_bf16_f32 v55, v50, v51
	s_nop 1
	v_permlane16_swap_b32_e32 v52, v54
	v_permlane16_swap_b32_e32 v53, v55
	v_cvt_pk_bf16_f32 v44, v44, v45
	v_cvt_pk_bf16_f32 v45, v46, v47
	v_cvt_pk_bf16_f32 v46, v40, v41
	v_cvt_pk_bf16_f32 v47, v42, v43
	s_nop 1
	v_permlane16_swap_b32_e32 v44, v46
	v_permlane16_swap_b32_e32 v45, v47
	v_cvt_pk_bf16_f32 v36, v36, v37
	v_cvt_pk_bf16_f32 v37, v38, v39
	v_cvt_pk_bf16_f32 v38, v32, v33
	v_cvt_pk_bf16_f32 v39, v34, v35
	s_nop 1
	v_permlane16_swap_b32_e32 v36, v38
	v_permlane16_swap_b32_e32 v37, v39
	v_cvt_pk_bf16_f32 v28, v28, v29
	v_cvt_pk_bf16_f32 v29, v30, v31
	v_cvt_pk_bf16_f32 v30, v24, v25
	v_cvt_pk_bf16_f32 v31, v26, v27
	s_nop 1
	v_permlane16_swap_b32_e32 v28, v30
	v_permlane16_swap_b32_e32 v29, v31
	v_cvt_pk_bf16_f32 v20, v20, v21
	v_cvt_pk_bf16_f32 v21, v22, v23
	v_cvt_pk_bf16_f32 v22, v16, v17
	v_cvt_pk_bf16_f32 v23, v18, v19
	s_nop 1
	v_permlane16_swap_b32_e32 v20, v22
	v_permlane16_swap_b32_e32 v21, v23
	v_cvt_pk_bf16_f32 v12, v12, v13
	v_cvt_pk_bf16_f32 v13, v14, v15
	v_cvt_pk_bf16_f32 v14, v8, v9
	v_cvt_pk_bf16_f32 v15, v10, v11
	s_nop 1
	v_permlane16_swap_b32_e32 v12, v14
	v_permlane16_swap_b32_e32 v13, v15
	v_cvt_pk_bf16_f32 v4, v4, v5
	v_cvt_pk_bf16_f32 v5, v6, v7
	v_cvt_pk_bf16_f32 v6, v0, v1
	v_cvt_pk_bf16_f32 v7, v2, v3
	s_nop 1
	v_permlane16_swap_b32_e32 v4, v6
	v_permlane16_swap_b32_e32 v5, v7
	s_and_saveexec_b64 s[10:11], vcc
	s_cbranch_execz .LBB0_232
	flat_store_dwordx4 v[90:91], v[76:79]
	v_lshl_add_u64 v[90:91], v[90:91], 0, s[12:13]
	flat_store_dwordx4 v[90:91], v[68:71]
	v_lshl_add_u64 v[90:91], v[90:91], 0, s[12:13]
	flat_store_dwordx4 v[90:91], v[60:63]
	v_lshl_add_u64 v[90:91], v[90:91], 0, s[12:13]
	flat_store_dwordx4 v[90:91], v[52:55]
	v_lshl_add_u64 v[90:91], v[90:91], 0, s[12:13]
	flat_store_dwordx4 v[90:91], v[44:47]
	v_lshl_add_u64 v[90:91], v[90:91], 0, s[12:13]
	flat_store_dwordx4 v[90:91], v[36:39]
	v_lshl_add_u64 v[90:91], v[90:91], 0, s[12:13]
	flat_store_dwordx4 v[90:91], v[28:31]
	v_lshl_add_u64 v[90:91], v[90:91], 0, s[12:13]
	flat_store_dwordx4 v[90:91], v[20:23]
	v_lshl_add_u64 v[90:91], v[90:91], 0, s[12:13]
	flat_store_dwordx4 v[90:91], v[12:15]
	v_lshl_add_u64 v[90:91], v[90:91], 0, s[12:13]
	flat_store_dwordx4 v[90:91], v[4:7]
	s_branch .LBB0_232

.Lg160o_epi:
	s_mulk_i32 s15, 0xa0
	v_or_b32_e32 v90, s15, v96
	s_mov_b32 s9, s45
	v_ashrrev_i32_e32 v91, 31, v90
	v_lshl_add_u64 v[92:93], v[84:85], 0, s[8:9]
	v_lshlrev_b64 v[94:95], 10, v[90:91]
	v_lshl_add_u64 v[94:95], v[94:95], 0, v[92:93]
	s_barrier
	v_lshl_add_u64 v[94:95], v[94:95], 1, s[6:7]
	v_bfe_u32 v90, v222, 4, 1
	v_mul_u32_u24_e32 v90, 24, v90
	v_mov_b32_e32 v91, 0
	v_lshl_add_u64 v[94:95], v[90:91], 0, v[94:95]
	s_mov_b64 s[12:13], 0x8000
	v_cvt_pk_bf16_f32 v76, v76, v77
	v_cvt_pk_bf16_f32 v77, v78, v79
	v_cvt_pk_bf16_f32 v78, v72, v73
	v_cvt_pk_bf16_f32 v79, v74, v75
	s_nop 1
	v_permlane16_swap_b32_e32 v76, v78
	v_permlane16_swap_b32_e32 v77, v79
	flat_store_dwordx4 v[94:95], v[76:79]
	v_lshl_add_u64 v[94:95], v[94:95], 0, s[12:13]
	v_cvt_pk_bf16_f32 v68, v68, v69
	v_cvt_pk_bf16_f32 v69, v70, v71
	v_cvt_pk_bf16_f32 v70, v64, v65
	v_cvt_pk_bf16_f32 v71, v66, v67
	s_nop 1
	v_permlane16_swap_b32_e32 v68, v70
	v_permlane16_swap_b32_e32 v69, v71
	flat_store_dwordx4 v[94:95], v[68:71]
	v_lshl_add_u64 v[94:95], v[94:95], 0, s[12:13]
	v_cvt_pk_bf16_f32 v60, v60, v61
	v_cvt_pk_bf16_f32 v61, v62, v63
	v_cvt_pk_bf16_f32 v62, v56, v57
	v_cvt_pk_bf16_f32 v63, v58, v59
	s_nop 1
	v_permlane16_swap_b32_e32 v60, v62
	v_permlane16_swap_b32_e32 v61, v63
	flat_store_dwordx4 v[94:95], v[60:63]
	v_lshl_add_u64 v[94:95], v[94:95], 0, s[12:13]
	v_cvt_pk_bf16_f32 v52, v52, v53
	v_cvt_pk_bf16_f32 v53, v54, v55
	v_cvt_pk_bf16_f32 v54, v48, v49
	v_cvt_pk_bf16_f32 v55, v50, v51
	s_nop 1
	v_permlane16_swap_b32_e32 v52, v54
	v_permlane16_swap_b32_e32 v53, v55
	flat_store_dwordx4 v[94:95], v[52:55]
	v_lshl_add_u64 v[94:95], v[94:95], 0, s[12:13]
	v_cvt_pk_bf16_f32 v44, v44, v45
	v_cvt_pk_bf16_f32 v45, v46, v47
	v_cvt_pk_bf16_f32 v46, v40, v41
	v_cvt_pk_bf16_f32 v47, v42, v43
	s_nop 1
	v_permlane16_swap_b32_e32 v44, v46
	v_permlane16_swap_b32_e32 v45, v47
	flat_store_dwordx4 v[94:95], v[44:47]
	v_lshl_add_u64 v[94:95], v[94:95], 0, s[12:13]
	v_cvt_pk_bf16_f32 v36, v36, v37
	v_cvt_pk_bf16_f32 v37, v38, v39
	v_cvt_pk_bf16_f32 v38, v32, v33
	v_cvt_pk_bf16_f32 v39, v34, v35
	s_nop 1
	v_permlane16_swap_b32_e32 v36, v38
	v_permlane16_swap_b32_e32 v37, v39
	flat_store_dwordx4 v[94:95], v[36:39]
	v_lshl_add_u64 v[94:95], v[94:95], 0, s[12:13]
	v_cvt_pk_bf16_f32 v28, v28, v29
	v_cvt_pk_bf16_f32 v29, v30, v31
	v_cvt_pk_bf16_f32 v30, v24, v25
	v_cvt_pk_bf16_f32 v31, v26, v27
	s_nop 1
	v_permlane16_swap_b32_e32 v28, v30
	v_permlane16_swap_b32_e32 v29, v31
	flat_store_dwordx4 v[94:95], v[28:31]
	v_lshl_add_u64 v[94:95], v[94:95], 0, s[12:13]
	v_cvt_pk_bf16_f32 v20, v20, v21
	v_cvt_pk_bf16_f32 v21, v22, v23
	v_cvt_pk_bf16_f32 v22, v16, v17
	v_cvt_pk_bf16_f32 v23, v18, v19
	s_nop 1
	v_permlane16_swap_b32_e32 v20, v22
	v_permlane16_swap_b32_e32 v21, v23
	flat_store_dwordx4 v[94:95], v[20:23]
	v_lshl_add_u64 v[94:95], v[94:95], 0, s[12:13]
	v_cvt_pk_bf16_f32 v12, v12, v13
	v_cvt_pk_bf16_f32 v13, v14, v15
	v_cvt_pk_bf16_f32 v14, v8, v9
	v_cvt_pk_bf16_f32 v15, v10, v11
	s_nop 1
	v_permlane16_swap_b32_e32 v12, v14
	v_permlane16_swap_b32_e32 v13, v15
	flat_store_dwordx4 v[94:95], v[12:15]
	v_lshl_add_u64 v[94:95], v[94:95], 0, s[12:13]
	v_cvt_pk_bf16_f32 v4, v4, v5
	v_cvt_pk_bf16_f32 v5, v6, v7
	v_cvt_pk_bf16_f32 v6, v0, v1
	v_cvt_pk_bf16_f32 v7, v2, v3
	s_nop 1
	v_permlane16_swap_b32_e32 v4, v6
	v_permlane16_swap_b32_e32 v5, v7
	flat_store_dwordx4 v[94:95], v[4:7]
	s_add_i32 s14, s14, 1
	s_mov_b32 s100, s101
	s_mov_b64 s[8:9], 0
